# gated conv a/b rows (20 of its 38 loads) loaded by the attention's last unit into its next-unit prefetch slots; conv re-mapped to consume them
# baseline (speedup 1.0000x reference)
.Latt_vw_go:
	v_add_u32_e32 v0, 0x3c00, v231
	ds_write_b128 v0, v[4:7]
	ds_write_b128 v0, v[8:11] offset:9216
	v_add_u32_e32 v0, 0x8400, v231
	ds_write_b128 v0, v[12:15]
	ds_write_b128 v0, v[16:19] offset:9216
	v_add_u32_e32 v0, 0xcc00, v231
	ds_write_b128 v0, v[20:23]
	ds_write_b128 v0, v[24:27] offset:9216
	v_add_u32_e32 v0, 0x11400, v231
	ds_write_b128 v0, v[28:31]
	ds_write_b128 v0, v[32:35] offset:9216
	v_add_u32_e32 v0, 0x15c00, v231
	ds_write_b128 v0, v[36:39]
	ds_write_b128 v0, v[40:43] offset:9216
	v_add_u32_e32 v0, 0x1a400, v231
	ds_write_b128 v0, v[44:47]
	ds_write_b128 v0, v[48:51] offset:9216
	v_add_u32_e32 v0, 0x1ec00, v231
	ds_write_b128 v0, v[52:55]
	ds_write_b128 v0, v[56:59] offset:9216
	v_mov_b32_e32 v251, 0xf149f2ca
	v_mov_b32_e32 v252, 0x3db504f3
	v_mov_b32_e32 v254, 0x3fb8aa3b
	v_add_u32_e32 v156, s67, v240
	v_add_u32_e32 v157, s67, v241
	v_add_u32_e32 v158, s67, v242
	v_add_u32_e32 v159, s67, v243
	v_add_u32_e32 v160, s67, v244
	v_add_u32_e32 v161, s67, v245
	v_add_u32_e32 v162, s67, v246
	v_add_u32_e32 v163, s67, v247
	v_mov_b32_e32 v248, 0xff61b1e6
	ds_read_b32 v164, v156 offset:0
	ds_read_b32 v165, v157 offset:0
	ds_read_b32 v166, v158 offset:0
	ds_read_b32 v167, v159 offset:0
	ds_read_b32 v168, v160 offset:0
	ds_read_b32 v169, v161 offset:0
	ds_read_b32 v170, v162 offset:0
	ds_read_b32 v171, v163 offset:0
	s_waitcnt lgkmcnt(0)
	ds_read_b32 v172, v156 offset:124
	ds_read_b32 v173, v157 offset:124
	ds_read_b32 v174, v158 offset:124
	ds_read_b32 v175, v159 offset:124
	ds_read_b32 v176, v160 offset:124
	ds_read_b32 v177, v161 offset:124
	ds_read_b32 v178, v162 offset:124
	ds_read_b32 v179, v163 offset:124
	v_pk_fma_f32 v[92:93], v[92:93], v[252:253], v[164:165] op_sel_hi:[1,0,1]
	v_pk_fma_f32 v[94:95], v[94:95], v[252:253], v[166:167] op_sel_hi:[1,0,1]
	v_pk_fma_f32 v[96:97], v[96:97], v[252:253], v[168:169] op_sel_hi:[1,0,1]
	v_pk_fma_f32 v[98:99], v[98:99], v[252:253], v[170:171] op_sel_hi:[1,0,1]
	v_cndmask_b32_e64 v92, v251, v92, s[4:5]
	v_cndmask_b32_e64 v93, v251, v93, s[6:7]
	v_cndmask_b32_e64 v94, v251, v94, s[8:9]
	v_cndmask_b32_e64 v95, v251, v95, s[10:11]
	v_cndmask_b32_e64 v96, v251, v96, s[12:13]
	v_cndmask_b32_e64 v97, v251, v97, s[14:15]
	v_cndmask_b32_e64 v98, v251, v98, s[16:17]
	v_cndmask_b32_e64 v99, v251, v99, s[18:19]
	v_max3_f32 v248, v248, v92, v93
	v_max3_f32 v248, v248, v94, v95
	v_max3_f32 v248, v248, v96, v97
	v_max3_f32 v248, v248, v98, v99
	s_waitcnt lgkmcnt(0)
	ds_read_b32 v164, v156 offset:248
	ds_read_b32 v165, v157 offset:248
	ds_read_b32 v166, v158 offset:248
	ds_read_b32 v167, v159 offset:248
	ds_read_b32 v168, v160 offset:248
	ds_read_b32 v169, v161 offset:248
	ds_read_b32 v170, v162 offset:248
	ds_read_b32 v171, v163 offset:248
	v_pk_fma_f32 v[100:101], v[100:101], v[252:253], v[172:173] op_sel_hi:[1,0,1]
	v_pk_fma_f32 v[102:103], v[102:103], v[252:253], v[174:175] op_sel_hi:[1,0,1]
	v_pk_fma_f32 v[104:105], v[104:105], v[252:253], v[176:177] op_sel_hi:[1,0,1]
	v_pk_fma_f32 v[106:107], v[106:107], v[252:253], v[178:179] op_sel_hi:[1,0,1]
	v_cndmask_b32_e64 v100, v251, v100, s[4:5]
	v_cndmask_b32_e64 v101, v251, v101, s[6:7]
	v_cndmask_b32_e64 v102, v251, v102, s[8:9]
	v_cndmask_b32_e64 v103, v251, v103, s[10:11]
	v_cndmask_b32_e64 v104, v251, v104, s[12:13]
	v_cndmask_b32_e64 v105, v251, v105, s[14:15]
	v_cndmask_b32_e64 v106, v251, v106, s[16:17]
	v_cndmask_b32_e64 v107, v251, v107, s[18:19]
	v_max3_f32 v248, v248, v100, v101
	v_max3_f32 v248, v248, v102, v103
	v_max3_f32 v248, v248, v104, v105
	v_max3_f32 v248, v248, v106, v107
	s_waitcnt lgkmcnt(0)
	ds_read_b32 v172, v156 offset:372
	ds_read_b32 v173, v157 offset:372
	ds_read_b32 v174, v158 offset:372
	ds_read_b32 v175, v159 offset:372
	ds_read_b32 v176, v160 offset:372
	ds_read_b32 v177, v161 offset:372
	ds_read_b32 v178, v162 offset:372
	ds_read_b32 v179, v163 offset:372
	v_pk_fma_f32 v[108:109], v[108:109], v[252:253], v[164:165] op_sel_hi:[1,0,1]
	v_pk_fma_f32 v[110:111], v[110:111], v[252:253], v[166:167] op_sel_hi:[1,0,1]
	v_pk_fma_f32 v[112:113], v[112:113], v[252:253], v[168:169] op_sel_hi:[1,0,1]
	v_pk_fma_f32 v[114:115], v[114:115], v[252:253], v[170:171] op_sel_hi:[1,0,1]
	v_cndmask_b32_e64 v108, v251, v108, s[4:5]
	v_cndmask_b32_e64 v109, v251, v109, s[6:7]
	v_cndmask_b32_e64 v110, v251, v110, s[8:9]
	v_cndmask_b32_e64 v111, v251, v111, s[10:11]
	v_cndmask_b32_e64 v112, v251, v112, s[12:13]
	v_cndmask_b32_e64 v113, v251, v113, s[14:15]
	v_cndmask_b32_e64 v114, v251, v114, s[16:17]
	v_cndmask_b32_e64 v115, v251, v115, s[18:19]
	v_max3_f32 v248, v248, v108, v109
	v_max3_f32 v248, v248, v110, v111
	v_max3_f32 v248, v248, v112, v113
	v_max3_f32 v248, v248, v114, v115
	s_waitcnt lgkmcnt(0)
	ds_read_b32 v164, v156 offset:496
	ds_read_b32 v165, v157 offset:496
	ds_read_b32 v166, v158 offset:496
	ds_read_b32 v167, v159 offset:496
	ds_read_b32 v168, v160 offset:496
	ds_read_b32 v169, v161 offset:496
	ds_read_b32 v170, v162 offset:496
	ds_read_b32 v171, v163 offset:496
	v_pk_fma_f32 v[116:117], v[116:117], v[252:253], v[172:173] op_sel_hi:[1,0,1]
	v_pk_fma_f32 v[118:119], v[118:119], v[252:253], v[174:175] op_sel_hi:[1,0,1]
	v_pk_fma_f32 v[120:121], v[120:121], v[252:253], v[176:177] op_sel_hi:[1,0,1]
	v_pk_fma_f32 v[122:123], v[122:123], v[252:253], v[178:179] op_sel_hi:[1,0,1]
	v_cndmask_b32_e64 v116, v251, v116, s[4:5]
	v_cndmask_b32_e64 v117, v251, v117, s[6:7]
	v_cndmask_b32_e64 v118, v251, v118, s[8:9]
	v_cndmask_b32_e64 v119, v251, v119, s[10:11]
	v_cndmask_b32_e64 v120, v251, v120, s[12:13]
	v_cndmask_b32_e64 v121, v251, v121, s[14:15]
	v_cndmask_b32_e64 v122, v251, v122, s[16:17]
	v_cndmask_b32_e64 v123, v251, v123, s[18:19]
	v_max3_f32 v248, v248, v116, v117
	v_max3_f32 v248, v248, v118, v119
	v_max3_f32 v248, v248, v120, v121
	v_max3_f32 v248, v248, v122, v123
	s_waitcnt lgkmcnt(0)
	ds_read_b32 v172, v156 offset:620
	ds_read_b32 v173, v157 offset:620
	ds_read_b32 v174, v158 offset:620
	ds_read_b32 v175, v159 offset:620
	ds_read_b32 v176, v160 offset:620
	ds_read_b32 v177, v161 offset:620
	ds_read_b32 v178, v162 offset:620
	ds_read_b32 v179, v163 offset:620
	v_pk_fma_f32 v[124:125], v[124:125], v[252:253], v[164:165] op_sel_hi:[1,0,1]
	v_pk_fma_f32 v[126:127], v[126:127], v[252:253], v[166:167] op_sel_hi:[1,0,1]
	v_pk_fma_f32 v[128:129], v[128:129], v[252:253], v[168:169] op_sel_hi:[1,0,1]
	v_pk_fma_f32 v[130:131], v[130:131], v[252:253], v[170:171] op_sel_hi:[1,0,1]
	v_cndmask_b32_e64 v124, v251, v124, s[4:5]
	v_cndmask_b32_e64 v125, v251, v125, s[6:7]
	v_cndmask_b32_e64 v126, v251, v126, s[8:9]
	v_cndmask_b32_e64 v127, v251, v127, s[10:11]
	v_cndmask_b32_e64 v128, v251, v128, s[12:13]
	v_cndmask_b32_e64 v129, v251, v129, s[14:15]
	v_cndmask_b32_e64 v130, v251, v130, s[16:17]
	v_cndmask_b32_e64 v131, v251, v131, s[18:19]
	v_max3_f32 v248, v248, v124, v125
	v_max3_f32 v248, v248, v126, v127
	v_max3_f32 v248, v248, v128, v129
	v_max3_f32 v248, v248, v130, v131
	s_waitcnt lgkmcnt(0)
	ds_read_b32 v164, v156 offset:744
	ds_read_b32 v165, v157 offset:744
	ds_read_b32 v166, v158 offset:744
	ds_read_b32 v167, v159 offset:744
	ds_read_b32 v168, v160 offset:744
	ds_read_b32 v169, v161 offset:744
	ds_read_b32 v170, v162 offset:744
	ds_read_b32 v171, v163 offset:744
	v_pk_fma_f32 v[132:133], v[132:133], v[252:253], v[172:173] op_sel_hi:[1,0,1]
	v_pk_fma_f32 v[134:135], v[134:135], v[252:253], v[174:175] op_sel_hi:[1,0,1]
	v_pk_fma_f32 v[136:137], v[136:137], v[252:253], v[176:177] op_sel_hi:[1,0,1]
	v_pk_fma_f32 v[138:139], v[138:139], v[252:253], v[178:179] op_sel_hi:[1,0,1]
	v_cndmask_b32_e64 v132, v251, v132, s[4:5]
	v_cndmask_b32_e64 v133, v251, v133, s[6:7]
	v_cndmask_b32_e64 v134, v251, v134, s[8:9]
	v_cndmask_b32_e64 v135, v251, v135, s[10:11]
	v_cndmask_b32_e64 v136, v251, v136, s[12:13]
	v_cndmask_b32_e64 v137, v251, v137, s[14:15]
	v_cndmask_b32_e64 v138, v251, v138, s[16:17]
	v_cndmask_b32_e64 v139, v251, v139, s[18:19]
	v_max3_f32 v248, v248, v132, v133
	v_max3_f32 v248, v248, v134, v135
	v_max3_f32 v248, v248, v136, v137
	v_max3_f32 v248, v248, v138, v139
	s_waitcnt lgkmcnt(0)
	ds_read_b32 v172, v156 offset:868
	ds_read_b32 v173, v157 offset:868
	ds_read_b32 v174, v158 offset:868
	ds_read_b32 v175, v159 offset:868
	ds_read_b32 v176, v160 offset:868
	ds_read_b32 v177, v161 offset:868
	ds_read_b32 v178, v162 offset:868
	ds_read_b32 v179, v163 offset:868
	v_pk_fma_f32 v[140:141], v[140:141], v[252:253], v[164:165] op_sel_hi:[1,0,1]
	v_pk_fma_f32 v[142:143], v[142:143], v[252:253], v[166:167] op_sel_hi:[1,0,1]
	v_pk_fma_f32 v[144:145], v[144:145], v[252:253], v[168:169] op_sel_hi:[1,0,1]
	v_pk_fma_f32 v[146:147], v[146:147], v[252:253], v[170:171] op_sel_hi:[1,0,1]
	v_cndmask_b32_e64 v140, v251, v140, s[4:5]
	v_cndmask_b32_e64 v141, v251, v141, s[6:7]
	v_cndmask_b32_e64 v142, v251, v142, s[8:9]
	v_cndmask_b32_e64 v143, v251, v143, s[10:11]
	v_cndmask_b32_e64 v144, v251, v144, s[12:13]
	v_cndmask_b32_e64 v145, v251, v145, s[14:15]
	v_cndmask_b32_e64 v146, v251, v146, s[16:17]
	v_cndmask_b32_e64 v147, v251, v147, s[18:19]
	v_max3_f32 v248, v248, v140, v141
	v_max3_f32 v248, v248, v142, v143
	v_max3_f32 v248, v248, v144, v145
	v_max3_f32 v248, v248, v146, v147
	s_waitcnt lgkmcnt(0)
	v_pk_fma_f32 v[148:149], v[148:149], v[252:253], v[172:173] op_sel_hi:[1,0,1]
	v_pk_fma_f32 v[150:151], v[150:151], v[252:253], v[174:175] op_sel_hi:[1,0,1]
	v_pk_fma_f32 v[152:153], v[152:153], v[252:253], v[176:177] op_sel_hi:[1,0,1]
	v_pk_fma_f32 v[154:155], v[154:155], v[252:253], v[178:179] op_sel_hi:[1,0,1]
	v_cndmask_b32_e64 v148, v251, v148, s[4:5]
	v_cndmask_b32_e64 v149, v251, v149, s[6:7]
	v_cndmask_b32_e64 v150, v251, v150, s[8:9]
	v_cndmask_b32_e64 v151, v251, v151, s[10:11]
	v_cndmask_b32_e64 v152, v251, v152, s[12:13]
	v_cndmask_b32_e64 v153, v251, v153, s[14:15]
	v_cndmask_b32_e64 v154, v251, v154, s[16:17]
	v_cndmask_b32_e64 v155, v251, v155, s[18:19]
	v_max3_f32 v248, v248, v148, v149
	v_max3_f32 v248, v248, v150, v151
	v_max3_f32 v248, v248, v152, v153
	v_max3_f32 v248, v248, v154, v155
	ds_bpermute_b32 v0, v238, v248
	s_waitcnt lgkmcnt(0)
	v_max_f32_e32 v248, v248, v0
	ds_bpermute_b32 v0, v239, v248
	s_waitcnt lgkmcnt(0)
	v_max_f32_e32 v248, v248, v0
	v_mov_b32_e32 v2, 0
	v_mov_b32_e32 v3, 0
	v_pk_add_f32 v[92:93], v[92:93], v[248:249] op_sel_hi:[1,0] neg_lo:[0,1] neg_hi:[0,1]
	v_pk_add_f32 v[94:95], v[94:95], v[248:249] op_sel_hi:[1,0] neg_lo:[0,1] neg_hi:[0,1]
	v_pk_add_f32 v[96:97], v[96:97], v[248:249] op_sel_hi:[1,0] neg_lo:[0,1] neg_hi:[0,1]
	v_pk_add_f32 v[98:99], v[98:99], v[248:249] op_sel_hi:[1,0] neg_lo:[0,1] neg_hi:[0,1]
	v_pk_mul_f32 v[92:93], v[92:93], v[254:255] op_sel_hi:[1,0]
	v_pk_mul_f32 v[94:95], v[94:95], v[254:255] op_sel_hi:[1,0]
	v_pk_mul_f32 v[96:97], v[96:97], v[254:255] op_sel_hi:[1,0]
	v_pk_mul_f32 v[98:99], v[98:99], v[254:255] op_sel_hi:[1,0]
	v_exp_f32_e32 v92, v92
	v_exp_f32_e32 v93, v93
	v_exp_f32_e32 v94, v94
	v_exp_f32_e32 v95, v95
	v_exp_f32_e32 v96, v96
	v_exp_f32_e32 v97, v97
	v_exp_f32_e32 v98, v98
	v_exp_f32_e32 v99, v99
	s_nop 0
	v_pk_add_f32 v[2:3], v[2:3], v[92:93]
	v_pk_add_f32 v[2:3], v[2:3], v[94:95]
	v_pk_add_f32 v[2:3], v[2:3], v[96:97]
	v_pk_add_f32 v[2:3], v[2:3], v[98:99]
	s_barrier
	s_add_i32 s30, s20, s46
	s_cmpk_lt_i32 s30, 0x200
	s_cbranch_scc0 .Latt_cvpf1
	s_and_b32 s69, s30, 7
	s_lshr_b32 s76, s30, 8
	s_lshl_b32 s69, s69, 1
	s_add_i32 s69, s69, s76
	s_lshl_b32 s69, s69, 12
	s_bfe_u32 s76, s30, 0x50003
	s_lshl_b32 s76, s76, 1
	s_add_i32 s77, s76, -4
	s_max_i32 s77, s77, 0
	s_min_i32 s77, s77, 56
	s_add_i32 s83, s76, -3
	s_max_i32 s83, s83, 0
	s_min_i32 s83, s83, 56
	s_add_i32 s83, s83, 8
	s_sub_i32 s83, s83, s77
	s_add_i32 s76, s76, s88
	s_lshl_b32 s77, s77, 6
	s_add_i32 s77, s77, s69
	s_lshl_b32 s77, s77, 8
	s_add_u32 s34, s50, s77
	s_addc_u32 s35, s51, 0
	s_add_u32 s34, s34, 0xe200000
	s_addc_u32 s35, s35, 0
	s_lshl_b32 s76, s76, 6
	s_add_i32 s76, s76, s69
	s_lshl_b32 s77, s92, 4
	s_add_i32 s76, s76, s77
	s_lshl_b32 s76, s76, 8
	s_add_u32 s36, s50, s76
	s_addc_u32 s37, s51, 0
	s_add_u32 s36, s36, 0xd200000
	s_addc_u32 s37, s37, 0
	global_load_dwordx4 v[76:79], v235, s[36:37] offset:0
	global_load_dwordx4 v[80:83], v235, s[36:37] offset:64
	global_load_dwordx4 v[84:87], v235, s[36:37] offset:128
	global_load_dwordx4 v[88:91], v235, s[36:37] offset:192
	global_load_dwordx4 v[4:7], v226, s[34:35]
	global_load_dwordx4 v[8:11], v227, s[34:35]
	s_add_u32 s34, s34, 0x4000
	s_addc_u32 s35, s35, 0
	global_load_dwordx4 v[12:15], v226, s[34:35]
	global_load_dwordx4 v[16:19], v227, s[34:35]
	s_add_u32 s34, s34, 0x4000
	s_addc_u32 s35, s35, 0
	global_load_dwordx4 v[20:23], v226, s[34:35]
	global_load_dwordx4 v[24:27], v227, s[34:35]
	s_add_u32 s34, s34, 0x4000
	s_addc_u32 s35, s35, 0
	global_load_dwordx4 v[28:31], v226, s[34:35]
	global_load_dwordx4 v[32:35], v227, s[34:35]
	s_add_u32 s34, s34, 0x4000
	s_addc_u32 s35, s35, 0
	global_load_dwordx4 v[36:39], v226, s[34:35]
	global_load_dwordx4 v[40:43], v227, s[34:35]
	s_add_u32 s34, s34, 0x4000
	s_addc_u32 s35, s35, 0
	global_load_dwordx4 v[44:47], v226, s[34:35]
	global_load_dwordx4 v[48:51], v227, s[34:35]
	s_add_u32 s34, s34, 0x4000
	s_addc_u32 s35, s35, 0
	global_load_dwordx4 v[52:55], v226, s[34:35]
	global_load_dwordx4 v[56:59], v227, s[34:35]
	s_add_u32 s34, s34, 0x4000
	s_addc_u32 s35, s35, 0
	s_branch .Latt_nopf1
.Latt_cvpf1:
	s_and_b32 s99, s66, 1
	s_lshr_b32 s100, s66, 1
	s_lshl_b32 s100, s100, 3
	s_mul_i32 s34, s100, 0x1800
	s_mul_hi_u32 s35, s100, 0x1800
	s_add_u32 s34, s50, s34
	s_addc_u32 s35, s51, s35
	s_add_u32 s34, s34, 0x12a00800
	s_addc_u32 s35, s35, 0
	s_lshl_b32 s99, s99, 10
	s_add_u32 s34, s34, s99
	s_addc_u32 s35, s35, 0
	s_lshl_b32 s99, s91, 10
	s_sub_u32 s34, s34, s99
	s_subb_u32 s35, s35, 0
	s_and_b32 s99, s100, 0xfff
	s_cmp_eq_u32 s99, 0
	s_cselect_b32 s99, 0, 0x1800
	s_sub_u32 s36, s34, s99
	s_subb_u32 s37, s35, 0
	global_load_dwordx4 v[4:7], v226, s[36:37]
	global_load_dwordx4 v[8:11], v226, s[36:37] offset:2048
	global_load_dwordx4 v[12:15], v226, s[34:35]
	global_load_dwordx4 v[16:19], v226, s[34:35] offset:2048
	s_add_u32 s34, s34, 0x1800
	s_addc_u32 s35, s35, 0
	global_load_dwordx4 v[20:23], v226, s[34:35]
	global_load_dwordx4 v[24:27], v226, s[34:35] offset:2048
	s_add_u32 s34, s34, 0x1800
	s_addc_u32 s35, s35, 0
	global_load_dwordx4 v[28:31], v226, s[34:35]
	global_load_dwordx4 v[32:35], v226, s[34:35] offset:2048
	s_add_u32 s34, s34, 0x1800
	s_addc_u32 s35, s35, 0
	global_load_dwordx4 v[36:39], v226, s[34:35]
	global_load_dwordx4 v[40:43], v226, s[34:35] offset:2048
	s_add_u32 s34, s34, 0x1800
	s_addc_u32 s35, s35, 0
	global_load_dwordx4 v[44:47], v226, s[34:35]
	global_load_dwordx4 v[48:51], v226, s[34:35] offset:2048
	s_add_u32 s34, s34, 0x1800
	s_addc_u32 s35, s35, 0
	global_load_dwordx4 v[52:55], v226, s[34:35]
	global_load_dwordx4 v[56:59], v226, s[34:35] offset:2048
	s_add_u32 s34, s34, 0x1800
	s_addc_u32 s35, s35, 0
	global_load_dwordx4 v[76:79], v226, s[34:35]
	global_load_dwordx4 v[80:83], v226, s[34:35] offset:2048
	s_add_u32 s34, s34, 0x1800
	s_addc_u32 s35, s35, 0
	global_load_dwordx4 v[84:87], v226, s[34:35]
	global_load_dwordx4 v[88:91], v226, s[34:35] offset:2048

.Latt_p6a_skip:
	s_barrier
	s_waitcnt vmcnt(26)
	v_add_u32_e32 v0, 0x3c00, v231
	ds_write_b128 v0, v[60:63]
	ds_write_b128 v0, v[64:67] offset:9216
	s_cmp_lt_u32 s28, 9
	s_cbranch_scc1 .Latt_vw8_skip
	v_add_u32_e32 v0, 0x8400, v231
	ds_write_b128 v0, v[68:71]
	ds_write_b128 v0, v[72:75] offset:9216
.Latt_vw8_skip:
	s_waitcnt lgkmcnt(0)
	s_barrier
	s_add_i32 s30, s20, s46
	s_cmpk_lt_i32 s30, 0x200
	s_cbranch_scc0 .Latt_cvpf3
	global_load_dwordx4 v[60:63], v226, s[34:35]
	global_load_dwordx4 v[64:67], v227, s[34:35]
	s_add_u32 s34, s34, 0x4000
	s_addc_u32 s35, s35, 0
	s_cmp_lt_u32 s83, 9
	s_cbranch_scc1 .Latt_k8_skip_g
	global_load_dwordx4 v[68:71], v226, s[34:35]
	global_load_dwordx4 v[72:75], v227, s[34:35]
.Latt_k8_skip_g:
	s_branch .Latt_nopf3
.Latt_cvpf3:
	s_add_i32 s99, s100, 7
	s_and_b32 s99, s99, 0xfff
	s_cmpk_eq_u32 s99, 0xfff
	s_cselect_b32 s99, 0, 0x1800
	s_add_u32 s34, s34, s99
	s_addc_u32 s35, s35, 0
	global_load_dwordx4 v[60:63], v226, s[34:35]
	global_load_dwordx4 v[64:67], v226, s[34:35] offset:2048

.Latt_p6b_skip:
	v_cvt_pk_bf16_f32 v220, v148, v149
	v_cvt_pk_bf16_f32 v221, v150, v151
	v_cvt_pk_bf16_f32 v222, v152, v153
	v_cvt_pk_bf16_f32 v223, v154, v155
	s_add_i32 s30, s27, 7
	s_add_i32 s31, s30, -7
	s_cmp_lt_i32 s30, 7
	s_cselect_b32 s30, s30, s31
	s_mul_i32 s30, s30, 0x4800
	s_add_i32 s30, s30, 0x3c00
	v_add_u32_e32 v0, s30, v233
	ds_read_b128 v[156:159], v0 offset:0
	ds_read_b128 v[160:163], v0 offset:2304
	ds_read_b128 v[164:167], v0 offset:4608
	ds_read_b128 v[168:171], v0 offset:6912
	ds_read_b128 v[172:175], v0 offset:9216
	ds_read_b128 v[176:179], v0 offset:11520
	ds_read_b128 v[180:183], v0 offset:13824
	ds_read_b128 v[184:187], v0 offset:16128
	s_waitcnt lgkmcnt(7)
	v_mfma_f32_16x16x32_bf16 v[188:191], v[156:159], v[220:223], v[188:191]
	s_waitcnt lgkmcnt(6)
	v_mfma_f32_16x16x32_bf16 v[192:195], v[160:163], v[220:223], v[192:195]
	s_waitcnt lgkmcnt(5)
	v_mfma_f32_16x16x32_bf16 v[196:199], v[164:167], v[220:223], v[196:199]
	s_waitcnt lgkmcnt(4)
	v_mfma_f32_16x16x32_bf16 v[200:203], v[168:171], v[220:223], v[200:203]
	s_waitcnt lgkmcnt(3)
	v_mfma_f32_16x16x32_bf16 v[204:207], v[172:175], v[220:223], v[204:207]
	s_waitcnt lgkmcnt(2)
	v_mfma_f32_16x16x32_bf16 v[208:211], v[176:179], v[220:223], v[208:211]
	s_waitcnt lgkmcnt(1)
	v_mfma_f32_16x16x32_bf16 v[212:215], v[180:183], v[220:223], v[212:215]
	s_waitcnt lgkmcnt(0)
	v_mfma_f32_16x16x32_bf16 v[216:219], v[184:187], v[220:223], v[216:219]
	v_add_f32_e32 v249, v2, v3
	ds_bpermute_b32 v0, v238, v249
	s_waitcnt lgkmcnt(0)
	v_add_f32_e32 v249, v249, v0
	ds_bpermute_b32 v0, v239, v249
	s_waitcnt lgkmcnt(0)
	v_add_f32_e32 v249, v249, v0
	v_div_scale_f32 v252, s[44:45], v249, v249, 1.0
	v_rcp_f32_e32 v253, v252
	v_div_scale_f32 v254, vcc, 1.0, v249, 1.0
	s_nop 0
	v_fma_f32 v255, -v252, v253, 1.0
	v_fmac_f32_e32 v253, v255, v253
	v_mul_f32_e32 v255, v254, v253
	v_fma_f32 v248, -v252, v255, v254
	v_fmac_f32_e32 v255, v248, v253
	v_fma_f32 v252, -v252, v255, v254
	v_div_fmas_f32 v252, v252, v253, v255
	v_div_fixup_f32 v252, v252, v249, 1.0
	s_nop 7
	v_pk_mul_f32 v[188:189], v[188:189], v[252:253] op_sel_hi:[1,0]
	v_pk_mul_f32 v[190:191], v[190:191], v[252:253] op_sel_hi:[1,0]
	v_pk_mul_f32 v[192:193], v[192:193], v[252:253] op_sel_hi:[1,0]
	v_pk_mul_f32 v[194:195], v[194:195], v[252:253] op_sel_hi:[1,0]
	v_pk_mul_f32 v[196:197], v[196:197], v[252:253] op_sel_hi:[1,0]
	v_pk_mul_f32 v[198:199], v[198:199], v[252:253] op_sel_hi:[1,0]
	v_pk_mul_f32 v[200:201], v[200:201], v[252:253] op_sel_hi:[1,0]
	v_pk_mul_f32 v[202:203], v[202:203], v[252:253] op_sel_hi:[1,0]
	v_pk_mul_f32 v[204:205], v[204:205], v[252:253] op_sel_hi:[1,0]
	v_pk_mul_f32 v[206:207], v[206:207], v[252:253] op_sel_hi:[1,0]
	v_pk_mul_f32 v[208:209], v[208:209], v[252:253] op_sel_hi:[1,0]
	v_pk_mul_f32 v[210:211], v[210:211], v[252:253] op_sel_hi:[1,0]
	v_pk_mul_f32 v[212:213], v[212:213], v[252:253] op_sel_hi:[1,0]
	v_pk_mul_f32 v[214:215], v[214:215], v[252:253] op_sel_hi:[1,0]
	v_pk_mul_f32 v[216:217], v[216:217], v[252:253] op_sel_hi:[1,0]
	v_pk_mul_f32 v[218:219], v[218:219], v[252:253] op_sel_hi:[1,0]
	v_pk_mul_f32 v[254:255], v[188:189], v[188:189]
	v_pk_fma_f32 v[254:255], v[190:191], v[190:191], v[254:255]
	v_pk_fma_f32 v[254:255], v[192:193], v[192:193], v[254:255]
	v_pk_fma_f32 v[254:255], v[194:195], v[194:195], v[254:255]
	v_pk_fma_f32 v[254:255], v[196:197], v[196:197], v[254:255]
	v_pk_fma_f32 v[254:255], v[198:199], v[198:199], v[254:255]
	v_pk_fma_f32 v[254:255], v[200:201], v[200:201], v[254:255]
	v_pk_fma_f32 v[254:255], v[202:203], v[202:203], v[254:255]
	v_pk_fma_f32 v[254:255], v[204:205], v[204:205], v[254:255]
	v_pk_fma_f32 v[254:255], v[206:207], v[206:207], v[254:255]
	v_pk_fma_f32 v[254:255], v[208:209], v[208:209], v[254:255]
	v_pk_fma_f32 v[254:255], v[210:211], v[210:211], v[254:255]
	v_pk_fma_f32 v[254:255], v[212:213], v[212:213], v[254:255]
	v_pk_fma_f32 v[254:255], v[214:215], v[214:215], v[254:255]
	v_pk_fma_f32 v[254:255], v[216:217], v[216:217], v[254:255]
	v_pk_fma_f32 v[254:255], v[218:219], v[218:219], v[254:255]
	v_add_f32_e32 v254, v254, v255
	ds_bpermute_b32 v253, v238, v254
	s_waitcnt lgkmcnt(0)
	v_add_f32_e32 v254, v254, v253
	ds_bpermute_b32 v253, v239, v254
	s_waitcnt lgkmcnt(0)
	v_add_f32_e32 v254, v254, v253
	v_mov_b32_e32 v253, 0x358637bd
	s_mov_b32 s30, 0x800000
	v_fmamk_f32 v254, v254, 0x3c000000, v253
	v_mul_f32_e32 v253, 0x4b800000, v254
	v_cmp_gt_f32_e32 vcc, s30, v254
	s_nop 1
	v_cndmask_b32_e32 v254, v254, v253, vcc
	v_rsq_f32_e32 v254, v254
	s_nop 0
	v_mul_f32_e32 v253, 0x45800000, v254
	v_cndmask_b32_e32 v254, v254, v253, vcc
	s_waitcnt vmcnt(2)
	v_pk_mul_f32 v[188:189], v[188:189], v[254:255] op_sel_hi:[1,0]
	v_pk_mul_f32 v[190:191], v[190:191], v[254:255] op_sel_hi:[1,0]
	v_pk_mul_f32 v[188:189], v[92:93], v[188:189]
	v_pk_mul_f32 v[190:191], v[94:95], v[190:191]
	v_cvt_pk_bf16_f32 v188, v188, v189
	v_cvt_pk_bf16_f32 v189, v190, v191
	global_store_dwordx2 v236, v[188:189], s[40:41] offset:0
	v_pk_mul_f32 v[192:193], v[192:193], v[254:255] op_sel_hi:[1,0]
	v_pk_mul_f32 v[194:195], v[194:195], v[254:255] op_sel_hi:[1,0]
	v_pk_mul_f32 v[192:193], v[96:97], v[192:193]
	v_pk_mul_f32 v[194:195], v[98:99], v[194:195]
	v_cvt_pk_bf16_f32 v192, v192, v193
	v_cvt_pk_bf16_f32 v193, v194, v195
	global_store_dwordx2 v236, v[192:193], s[40:41] offset:32
	v_pk_mul_f32 v[196:197], v[196:197], v[254:255] op_sel_hi:[1,0]
	v_pk_mul_f32 v[198:199], v[198:199], v[254:255] op_sel_hi:[1,0]
	v_pk_mul_f32 v[196:197], v[100:101], v[196:197]
	v_pk_mul_f32 v[198:199], v[102:103], v[198:199]
	v_cvt_pk_bf16_f32 v196, v196, v197
	v_cvt_pk_bf16_f32 v197, v198, v199
	global_store_dwordx2 v236, v[196:197], s[40:41] offset:64
	v_pk_mul_f32 v[200:201], v[200:201], v[254:255] op_sel_hi:[1,0]
	v_pk_mul_f32 v[202:203], v[202:203], v[254:255] op_sel_hi:[1,0]
	v_pk_mul_f32 v[200:201], v[104:105], v[200:201]
	v_pk_mul_f32 v[202:203], v[106:107], v[202:203]
	v_cvt_pk_bf16_f32 v200, v200, v201
	v_cvt_pk_bf16_f32 v201, v202, v203
	global_store_dwordx2 v236, v[200:201], s[40:41] offset:96
	v_pk_mul_f32 v[204:205], v[204:205], v[254:255] op_sel_hi:[1,0]
	v_pk_mul_f32 v[206:207], v[206:207], v[254:255] op_sel_hi:[1,0]
	v_pk_mul_f32 v[204:205], v[108:109], v[204:205]
	v_pk_mul_f32 v[206:207], v[110:111], v[206:207]
	v_cvt_pk_bf16_f32 v204, v204, v205
	v_cvt_pk_bf16_f32 v205, v206, v207
	global_store_dwordx2 v236, v[204:205], s[40:41] offset:128
	v_pk_mul_f32 v[208:209], v[208:209], v[254:255] op_sel_hi:[1,0]
	v_pk_mul_f32 v[210:211], v[210:211], v[254:255] op_sel_hi:[1,0]
	v_pk_mul_f32 v[208:209], v[112:113], v[208:209]
	v_pk_mul_f32 v[210:211], v[114:115], v[210:211]
	v_cvt_pk_bf16_f32 v208, v208, v209
	v_cvt_pk_bf16_f32 v209, v210, v211
	global_store_dwordx2 v236, v[208:209], s[40:41] offset:160
	v_pk_mul_f32 v[212:213], v[212:213], v[254:255] op_sel_hi:[1,0]
	v_pk_mul_f32 v[214:215], v[214:215], v[254:255] op_sel_hi:[1,0]
	v_pk_mul_f32 v[212:213], v[116:117], v[212:213]
	v_pk_mul_f32 v[214:215], v[118:119], v[214:215]
	v_cvt_pk_bf16_f32 v212, v212, v213
	v_cvt_pk_bf16_f32 v213, v214, v215
	global_store_dwordx2 v236, v[212:213], s[40:41] offset:192
	v_pk_mul_f32 v[216:217], v[216:217], v[254:255] op_sel_hi:[1,0]
	v_pk_mul_f32 v[218:219], v[218:219], v[254:255] op_sel_hi:[1,0]
	v_pk_mul_f32 v[216:217], v[120:121], v[216:217]
	v_pk_mul_f32 v[218:219], v[122:123], v[218:219]
	v_cvt_pk_bf16_f32 v216, v216, v217
	v_cvt_pk_bf16_f32 v217, v218, v219
	global_store_dwordx2 v236, v[216:217], s[40:41] offset:224
	s_barrier
	s_add_i32 s20, s20, s46
	s_cmpk_lt_i32 s20, 0x200
	s_cbranch_scc0 .Latt_done
	s_and_b32 s30, s20, 7
	s_lshr_b32 s31, s20, 8
	s_lshl_b32 s30, s30, 1
	s_add_i32 s30, s30, s31
	s_lshr_b32 s21, s30, 3
	s_and_b32 s22, s30, 7
	s_bfe_u32 s23, s20, 0x50003
	s_lshl_b32 s24, s23, 1
	s_add_i32 s24, s24, s88
	s_lshl_b32 s31, s23, 1
	s_add_i32 s25, s31, -4
	s_max_i32 s25, s25, 0
	s_min_i32 s25, s25, 56
	s_add_i32 s26, s24, -4
	s_max_i32 s26, s26, 0
	s_min_i32 s26, s26, 56
	s_sub_i32 s27, s26, s25
	s_add_i32 s28, s31, -3
	s_max_i32 s28, s28, 0
	s_min_i32 s28, s28, 56
	s_add_i32 s28, s28, 8
	s_sub_i32 s28, s28, s25
	s_lshl_b32 s31, s22, 20
	s_lshl_b32 s30, s21, 12
	s_add_i32 s31, s31, s30
	s_lshl_b32 s30, s25, 6
	s_add_i32 s31, s31, s30
	s_lshl_b32 s31, s31, 1
	s_add_u32 s38, s50, s31
	s_addc_u32 s39, s51, 0
	s_add_u32 s38, s38, 0xf200000
	s_addc_u32 s39, s39, 0
	s_lshl_b32 s31, s21, 12
	s_lshl_b32 s30, s24, 6
	s_add_i32 s31, s31, s30
	s_lshl_b32 s30, s92, 4
	s_add_i32 s31, s31, s30
	s_lshl_b32 s31, s31, 11
	s_lshl_b32 s30, s22, 7
	s_add_i32 s31, s31, s30
	s_lshl_b32 s31, s31, 1
	s_add_u32 s40, s74, s31
	s_addc_u32 s41, s75, 0
	s_lshl_b32 s31, s22, 9
	s_add_u32 s60, s96, s31
	s_addc_u32 s61, s97, 0
	s_sub_i32 s31, s26, s24
	s_add_i32 s31, s31, 7
	s_mul_i32 s31, s31, 31
	s_mul_i32 s67, s22, 465
	s_add_i32 s67, s67, s31
	s_lshl_b32 s67, s67, 2
	v_add_u32_e32 v0, 0x3c00, v228
	ds_write_b128 v0, v[4:7]
	ds_write_b128 v0, v[8:11] offset:8704
	v_add_u32_e32 v0, 0x8400, v228
	ds_write_b128 v0, v[12:15]
	ds_write_b128 v0, v[16:19] offset:8704
	v_add_u32_e32 v0, 0xcc00, v228
	ds_write_b128 v0, v[20:23]
	ds_write_b128 v0, v[24:27] offset:8704
	v_add_u32_e32 v0, 0x11400, v228
	ds_write_b128 v0, v[28:31]
	ds_write_b128 v0, v[32:35] offset:8704
	v_add_u32_e32 v0, 0x15c00, v228
	ds_write_b128 v0, v[36:39]
	ds_write_b128 v0, v[40:43] offset:8704
	v_add_u32_e32 v0, 0x1a400, v228
	ds_write_b128 v0, v[44:47]
	ds_write_b128 v0, v[48:51] offset:8704
	v_add_u32_e32 v0, 0x1ec00, v228
	ds_write_b128 v0, v[52:55]
	ds_write_b128 v0, v[56:59] offset:8704
	s_branch .Latt_unit

.Lcv_item:
	s_and_b32 s24, s20, 1
	s_lshr_b32 s21, s20, 1
	s_lshl_b32 s21, s21, 3
	s_lshl_b32 s25, s24, 11
	v_lshl_add_u32 v240, v234, 5, s25
	s_lshl_b32 s25, s24, 10
	v_lshl_add_u32 v241, v234, 4, s25
	s_and_b32 s26, s21, 0xfff
	s_add_i32 s27, s21, 7
	s_and_b32 s27, s27, 0xfff
	s_mul_i32 s24, s21, 0x1800
	s_mul_hi_u32 s25, s21, 0x1800
	s_add_u32 s28, s50, s24
	s_addc_u32 s29, s51, s25
	s_add_u32 s28, s28, 0x12a00800
	s_addc_u32 s29, s29, 0
	s_lshl_b32 s24, s21, 12
	s_add_u32 s18, s74, s24
	s_addc_u32 s19, s75, 0
	s_add_u32 s18, s18, 0x800
	s_addc_u32 s19, s19, 0
	global_load_dwordx4 v[92:95], v240, s[4:5]
	global_load_dwordx4 v[96:99], v240, s[4:5] offset:16
	global_load_dwordx4 v[100:103], v240, s[10:11]
	global_load_dwordx4 v[104:107], v240, s[10:11] offset:16
	global_load_dwordx4 v[108:111], v240, s[12:13]
	global_load_dwordx4 v[112:115], v240, s[12:13] offset:16
	global_load_dwordx4 v[116:119], v240, s[6:7]
	global_load_dwordx4 v[120:123], v240, s[6:7] offset:16
	global_load_dwordx4 v[124:127], v240, s[8:9]
	global_load_dwordx4 v[128:131], v240, s[8:9] offset:16
	s_mov_b64 s[22:23], s[28:29]
	global_load_dwordx4 v[132:135], v241, s[22:23] offset:-2048
	s_add_u32 s22, s22, 0x1800
	s_addc_u32 s23, s23, 0
	global_load_dwordx4 v[136:139], v241, s[22:23] offset:-2048
	s_add_u32 s22, s22, 0x1800
	s_addc_u32 s23, s23, 0
	global_load_dwordx4 v[140:143], v241, s[22:23] offset:-2048
	s_add_u32 s22, s22, 0x1800
	s_addc_u32 s23, s23, 0
	global_load_dwordx4 v[144:147], v241, s[22:23] offset:-2048
	s_add_u32 s22, s22, 0x1800
	s_addc_u32 s23, s23, 0
	global_load_dwordx4 v[148:151], v241, s[22:23] offset:-2048
	s_add_u32 s22, s22, 0x1800
	s_addc_u32 s23, s23, 0
	global_load_dwordx4 v[152:155], v241, s[22:23] offset:-2048
	s_add_u32 s22, s22, 0x1800
	s_addc_u32 s23, s23, 0
	global_load_dwordx4 v[156:159], v241, s[22:23] offset:-2048
	s_add_u32 s22, s22, 0x1800
	s_addc_u32 s23, s23, 0
	global_load_dwordx4 v[160:163], v241, s[22:23] offset:-2048
	s_mov_b32 s25, 0x800000
	s_waitcnt vmcnt(7)
	s_cmp_lg_u32 s26, 0
	s_cbranch_scc1 .Lcv_pv_ok
	v_mov_b32_e32 v4, 0
	v_mov_b32_e32 v8, 0
	v_mov_b32_e32 v5, 0
	v_mov_b32_e32 v9, 0
	v_mov_b32_e32 v6, 0
	v_mov_b32_e32 v10, 0
	v_mov_b32_e32 v7, 0
	v_mov_b32_e32 v11, 0
.Lcv_pv_ok:
	v_lshlrev_b32_e32 v188, 16, v4
	v_and_b32_e32 v189, 0xffff0000, v4
	v_lshlrev_b32_e32 v196, 16, v8
	v_and_b32_e32 v197, 0xffff0000, v8
	v_lshlrev_b32_e32 v190, 16, v5
	v_and_b32_e32 v191, 0xffff0000, v5
	v_lshlrev_b32_e32 v198, 16, v9
	v_and_b32_e32 v199, 0xffff0000, v9
	v_lshlrev_b32_e32 v192, 16, v6
	v_and_b32_e32 v193, 0xffff0000, v6
	v_lshlrev_b32_e32 v200, 16, v10
	v_and_b32_e32 v201, 0xffff0000, v10
	v_lshlrev_b32_e32 v194, 16, v7
	v_and_b32_e32 v195, 0xffff0000, v7
	v_lshlrev_b32_e32 v202, 16, v11
	v_and_b32_e32 v203, 0xffff0000, v11
	v_pk_mul_f32 v[164:165], v[188:189], v[196:197]
	v_pk_mul_f32 v[166:167], v[190:191], v[198:199]
	v_pk_mul_f32 v[168:169], v[192:193], v[200:201]
	v_pk_mul_f32 v[170:171], v[194:195], v[202:203]
	v_lshlrev_b32_e32 v188, 16, v12
	v_and_b32_e32 v189, 0xffff0000, v12
	v_lshlrev_b32_e32 v196, 16, v16
	v_and_b32_e32 v197, 0xffff0000, v16
	v_lshlrev_b32_e32 v190, 16, v13
	v_and_b32_e32 v191, 0xffff0000, v13
	v_lshlrev_b32_e32 v198, 16, v17
	v_and_b32_e32 v199, 0xffff0000, v17
	v_lshlrev_b32_e32 v192, 16, v14
	v_and_b32_e32 v193, 0xffff0000, v14
	v_lshlrev_b32_e32 v200, 16, v18
	v_and_b32_e32 v201, 0xffff0000, v18
	v_lshlrev_b32_e32 v194, 16, v15
	v_and_b32_e32 v195, 0xffff0000, v15
	v_lshlrev_b32_e32 v202, 16, v19
	v_and_b32_e32 v203, 0xffff0000, v19
	v_pk_mul_f32 v[172:173], v[188:189], v[196:197]
	v_pk_mul_f32 v[174:175], v[190:191], v[198:199]
	v_pk_mul_f32 v[176:177], v[192:193], v[200:201]
	v_pk_mul_f32 v[178:179], v[194:195], v[202:203]
	v_lshlrev_b32_e32 v188, 16, v20
	v_and_b32_e32 v189, 0xffff0000, v20
	v_lshlrev_b32_e32 v196, 16, v24
	v_and_b32_e32 v197, 0xffff0000, v24
	v_lshlrev_b32_e32 v190, 16, v21
	v_and_b32_e32 v191, 0xffff0000, v21
	v_lshlrev_b32_e32 v198, 16, v25
	v_and_b32_e32 v199, 0xffff0000, v25
	v_lshlrev_b32_e32 v192, 16, v22
	v_and_b32_e32 v193, 0xffff0000, v22
	v_lshlrev_b32_e32 v200, 16, v26
	v_and_b32_e32 v201, 0xffff0000, v26
	v_lshlrev_b32_e32 v194, 16, v23
	v_and_b32_e32 v195, 0xffff0000, v23
	v_lshlrev_b32_e32 v202, 16, v27
	v_and_b32_e32 v203, 0xffff0000, v27
	v_pk_mul_f32 v[180:181], v[188:189], v[196:197]
	v_pk_mul_f32 v[182:183], v[190:191], v[198:199]
	v_pk_mul_f32 v[184:185], v[192:193], v[200:201]
	v_pk_mul_f32 v[186:187], v[194:195], v[202:203]
	v_lshlrev_b32_e32 v204, 16, v132
	v_and_b32_e32 v205, 0xffff0000, v132
	v_lshlrev_b32_e32 v206, 16, v133
	v_and_b32_e32 v207, 0xffff0000, v133
	v_lshlrev_b32_e32 v208, 16, v134
	v_and_b32_e32 v209, 0xffff0000, v134
	v_lshlrev_b32_e32 v210, 16, v135
	v_and_b32_e32 v211, 0xffff0000, v135
	v_pk_mul_f32 v[68:69], v[100:101], v[172:173]
	v_pk_mul_f32 v[226:227], v[108:109], v[180:181]
	v_pk_mul_f32 v[70:71], v[102:103], v[174:175]
	v_pk_mul_f32 v[228:229], v[110:111], v[182:183]
	v_pk_mul_f32 v[72:73], v[104:105], v[176:177]
	v_pk_mul_f32 v[230:231], v[112:113], v[184:185]
	v_pk_mul_f32 v[74:75], v[106:107], v[178:179]
	v_pk_mul_f32 v[232:233], v[114:115], v[186:187]
	v_pk_fma_f32 v[212:213], v[92:93], v[164:165], v[68:69]
	v_pk_fma_f32 v[214:215], v[94:95], v[166:167], v[70:71]
	v_pk_fma_f32 v[216:217], v[96:97], v[168:169], v[72:73]
	v_pk_fma_f32 v[218:219], v[98:99], v[170:171], v[74:75]
	v_pk_add_f32 v[212:213], v[212:213], v[226:227]
	v_pk_add_f32 v[214:215], v[214:215], v[228:229]
	v_pk_add_f32 v[216:217], v[216:217], v[230:231]
	v_pk_add_f32 v[218:219], v[218:219], v[232:233]
	v_pk_add_f32 v[212:213], v[116:117], v[212:213]
	v_pk_add_f32 v[214:215], v[118:119], v[214:215]
	v_pk_add_f32 v[216:217], v[120:121], v[216:217]
	v_pk_add_f32 v[218:219], v[122:123], v[218:219]
	v_pk_mul_f32 v[212:213], v[212:213], v[204:205]
	v_pk_mul_f32 v[214:215], v[214:215], v[206:207]
	v_pk_mul_f32 v[216:217], v[216:217], v[208:209]
	v_pk_mul_f32 v[218:219], v[218:219], v[210:211]
	v_pk_mul_f32 v[244:245], v[212:213], v[212:213]
	v_pk_fma_f32 v[244:245], v[214:215], v[214:215], v[244:245]
	v_pk_fma_f32 v[244:245], v[216:217], v[216:217], v[244:245]
	v_pk_fma_f32 v[244:245], v[218:219], v[218:219], v[244:245]
	v_add_f32_e32 v244, v244, v245
	s_nop 1
	v_add_f32_dpp v244, v244, v244 quad_perm:[1,0,3,2] row_mask:0xf bank_mask:0xf
	s_nop 1
	v_add_f32_dpp v244, v244, v244 quad_perm:[2,3,0,1] row_mask:0xf bank_mask:0xf
	s_nop 1
	v_add_f32_dpp v244, v244, v244 row_half_mirror row_mask:0xf bank_mask:0xf
	s_nop 1
	v_add_f32_dpp v244, v244, v244 row_mirror row_mask:0xf bank_mask:0xf
	v_fmamk_f32 v246, v244, 0x3c000000, v242
	v_mul_f32_e32 v248, 0x4b800000, v246
	v_cmp_gt_f32_e32 vcc, s25, v246
	s_nop 1
	v_cndmask_b32_e32 v246, v246, v248, vcc
	v_rsq_f32_e32 v246, v246
	s_nop 0
	v_mul_f32_e32 v248, 0x45800000, v246
	v_cndmask_b32_e32 v246, v246, v248, vcc
	v_pk_mul_f32 v[212:213], v[212:213], v[246:247] op_sel_hi:[1,0]
	v_pk_mul_f32 v[214:215], v[214:215], v[246:247] op_sel_hi:[1,0]
	v_pk_mul_f32 v[216:217], v[216:217], v[246:247] op_sel_hi:[1,0]
	v_pk_mul_f32 v[218:219], v[218:219], v[246:247] op_sel_hi:[1,0]
	v_pk_mul_f32 v[212:213], v[124:125], v[212:213]
	v_pk_mul_f32 v[214:215], v[126:127], v[214:215]
	v_pk_mul_f32 v[216:217], v[128:129], v[216:217]
	v_pk_mul_f32 v[218:219], v[130:131], v[218:219]
	v_cvt_pk_bf16_f32 v68, v212, v213
	v_cvt_pk_bf16_f32 v69, v214, v215
	v_cvt_pk_bf16_f32 v70, v216, v217
	v_cvt_pk_bf16_f32 v71, v218, v219
	global_store_dwordx4 v241, v[68:71], s[18:19]
	s_add_u32 s18, s18, 0x1000
	s_addc_u32 s19, s19, 0
	s_waitcnt vmcnt(6)
	v_lshlrev_b32_e32 v188, 16, v28
	v_and_b32_e32 v189, 0xffff0000, v28
	v_lshlrev_b32_e32 v196, 16, v32
	v_and_b32_e32 v197, 0xffff0000, v32
	v_lshlrev_b32_e32 v190, 16, v29
	v_and_b32_e32 v191, 0xffff0000, v29
	v_lshlrev_b32_e32 v198, 16, v33
	v_and_b32_e32 v199, 0xffff0000, v33
	v_lshlrev_b32_e32 v192, 16, v30
	v_and_b32_e32 v193, 0xffff0000, v30
	v_lshlrev_b32_e32 v200, 16, v34
	v_and_b32_e32 v201, 0xffff0000, v34
	v_lshlrev_b32_e32 v194, 16, v31
	v_and_b32_e32 v195, 0xffff0000, v31
	v_lshlrev_b32_e32 v202, 16, v35
	v_and_b32_e32 v203, 0xffff0000, v35
	v_pk_mul_f32 v[164:165], v[188:189], v[196:197]
	v_pk_mul_f32 v[166:167], v[190:191], v[198:199]
	v_pk_mul_f32 v[168:169], v[192:193], v[200:201]
	v_pk_mul_f32 v[170:171], v[194:195], v[202:203]
	v_lshlrev_b32_e32 v204, 16, v136
	v_and_b32_e32 v205, 0xffff0000, v136
	v_lshlrev_b32_e32 v206, 16, v137
	v_and_b32_e32 v207, 0xffff0000, v137
	v_lshlrev_b32_e32 v208, 16, v138
	v_and_b32_e32 v209, 0xffff0000, v138
	v_lshlrev_b32_e32 v210, 16, v139
	v_and_b32_e32 v211, 0xffff0000, v139
	v_pk_mul_f32 v[68:69], v[100:101], v[180:181]
	v_pk_mul_f32 v[226:227], v[108:109], v[164:165]
	v_pk_mul_f32 v[70:71], v[102:103], v[182:183]
	v_pk_mul_f32 v[228:229], v[110:111], v[166:167]
	v_pk_mul_f32 v[72:73], v[104:105], v[184:185]
	v_pk_mul_f32 v[230:231], v[112:113], v[168:169]
	v_pk_mul_f32 v[74:75], v[106:107], v[186:187]
	v_pk_mul_f32 v[232:233], v[114:115], v[170:171]
	v_pk_fma_f32 v[212:213], v[92:93], v[172:173], v[68:69]
	v_pk_fma_f32 v[214:215], v[94:95], v[174:175], v[70:71]
	v_pk_fma_f32 v[216:217], v[96:97], v[176:177], v[72:73]
	v_pk_fma_f32 v[218:219], v[98:99], v[178:179], v[74:75]
	v_pk_add_f32 v[212:213], v[212:213], v[226:227]
	v_pk_add_f32 v[214:215], v[214:215], v[228:229]
	v_pk_add_f32 v[216:217], v[216:217], v[230:231]
	v_pk_add_f32 v[218:219], v[218:219], v[232:233]
	v_pk_add_f32 v[212:213], v[116:117], v[212:213]
	v_pk_add_f32 v[214:215], v[118:119], v[214:215]
	v_pk_add_f32 v[216:217], v[120:121], v[216:217]
	v_pk_add_f32 v[218:219], v[122:123], v[218:219]
	v_pk_mul_f32 v[212:213], v[212:213], v[204:205]
	v_pk_mul_f32 v[214:215], v[214:215], v[206:207]
	v_pk_mul_f32 v[216:217], v[216:217], v[208:209]
	v_pk_mul_f32 v[218:219], v[218:219], v[210:211]
	v_pk_mul_f32 v[244:245], v[212:213], v[212:213]
	v_pk_fma_f32 v[244:245], v[214:215], v[214:215], v[244:245]
	v_pk_fma_f32 v[244:245], v[216:217], v[216:217], v[244:245]
	v_pk_fma_f32 v[244:245], v[218:219], v[218:219], v[244:245]
	v_add_f32_e32 v244, v244, v245
	s_nop 1
	v_add_f32_dpp v244, v244, v244 quad_perm:[1,0,3,2] row_mask:0xf bank_mask:0xf
	s_nop 1
	v_add_f32_dpp v244, v244, v244 quad_perm:[2,3,0,1] row_mask:0xf bank_mask:0xf
	s_nop 1
	v_add_f32_dpp v244, v244, v244 row_half_mirror row_mask:0xf bank_mask:0xf
	s_nop 1
	v_add_f32_dpp v244, v244, v244 row_mirror row_mask:0xf bank_mask:0xf
	v_fmamk_f32 v246, v244, 0x3c000000, v242
	v_mul_f32_e32 v248, 0x4b800000, v246
	v_cmp_gt_f32_e32 vcc, s25, v246
	s_nop 1
	v_cndmask_b32_e32 v246, v246, v248, vcc
	v_rsq_f32_e32 v246, v246
	s_nop 0
	v_mul_f32_e32 v248, 0x45800000, v246
	v_cndmask_b32_e32 v246, v246, v248, vcc
	v_pk_mul_f32 v[212:213], v[212:213], v[246:247] op_sel_hi:[1,0]
	v_pk_mul_f32 v[214:215], v[214:215], v[246:247] op_sel_hi:[1,0]
	v_pk_mul_f32 v[216:217], v[216:217], v[246:247] op_sel_hi:[1,0]
	v_pk_mul_f32 v[218:219], v[218:219], v[246:247] op_sel_hi:[1,0]
	v_pk_mul_f32 v[212:213], v[124:125], v[212:213]
	v_pk_mul_f32 v[214:215], v[126:127], v[214:215]
	v_pk_mul_f32 v[216:217], v[128:129], v[216:217]
	v_pk_mul_f32 v[218:219], v[130:131], v[218:219]
	v_cvt_pk_bf16_f32 v68, v212, v213
	v_cvt_pk_bf16_f32 v69, v214, v215
	v_cvt_pk_bf16_f32 v70, v216, v217
	v_cvt_pk_bf16_f32 v71, v218, v219
	global_store_dwordx4 v241, v[68:71], s[18:19]
	s_add_u32 s18, s18, 0x1000
	s_addc_u32 s19, s19, 0
	s_waitcnt vmcnt(5)
	v_lshlrev_b32_e32 v188, 16, v36
	v_and_b32_e32 v189, 0xffff0000, v36
	v_lshlrev_b32_e32 v196, 16, v40
	v_and_b32_e32 v197, 0xffff0000, v40
	v_lshlrev_b32_e32 v190, 16, v37
	v_and_b32_e32 v191, 0xffff0000, v37
	v_lshlrev_b32_e32 v198, 16, v41
	v_and_b32_e32 v199, 0xffff0000, v41
	v_lshlrev_b32_e32 v192, 16, v38
	v_and_b32_e32 v193, 0xffff0000, v38
	v_lshlrev_b32_e32 v200, 16, v42
	v_and_b32_e32 v201, 0xffff0000, v42
	v_lshlrev_b32_e32 v194, 16, v39
	v_and_b32_e32 v195, 0xffff0000, v39
	v_lshlrev_b32_e32 v202, 16, v43
	v_and_b32_e32 v203, 0xffff0000, v43
	v_pk_mul_f32 v[172:173], v[188:189], v[196:197]
	v_pk_mul_f32 v[174:175], v[190:191], v[198:199]
	v_pk_mul_f32 v[176:177], v[192:193], v[200:201]
	v_pk_mul_f32 v[178:179], v[194:195], v[202:203]
	v_lshlrev_b32_e32 v204, 16, v140
	v_and_b32_e32 v205, 0xffff0000, v140
	v_lshlrev_b32_e32 v206, 16, v141
	v_and_b32_e32 v207, 0xffff0000, v141
	v_lshlrev_b32_e32 v208, 16, v142
	v_and_b32_e32 v209, 0xffff0000, v142
	v_lshlrev_b32_e32 v210, 16, v143
	v_and_b32_e32 v211, 0xffff0000, v143
	v_pk_mul_f32 v[68:69], v[100:101], v[164:165]
	v_pk_mul_f32 v[226:227], v[108:109], v[172:173]
	v_pk_mul_f32 v[70:71], v[102:103], v[166:167]
	v_pk_mul_f32 v[228:229], v[110:111], v[174:175]
	v_pk_mul_f32 v[72:73], v[104:105], v[168:169]
	v_pk_mul_f32 v[230:231], v[112:113], v[176:177]
	v_pk_mul_f32 v[74:75], v[106:107], v[170:171]
	v_pk_mul_f32 v[232:233], v[114:115], v[178:179]
	v_pk_fma_f32 v[212:213], v[92:93], v[180:181], v[68:69]
	v_pk_fma_f32 v[214:215], v[94:95], v[182:183], v[70:71]
	v_pk_fma_f32 v[216:217], v[96:97], v[184:185], v[72:73]
	v_pk_fma_f32 v[218:219], v[98:99], v[186:187], v[74:75]
	v_pk_add_f32 v[212:213], v[212:213], v[226:227]
	v_pk_add_f32 v[214:215], v[214:215], v[228:229]
	v_pk_add_f32 v[216:217], v[216:217], v[230:231]
	v_pk_add_f32 v[218:219], v[218:219], v[232:233]
	v_pk_add_f32 v[212:213], v[116:117], v[212:213]
	v_pk_add_f32 v[214:215], v[118:119], v[214:215]
	v_pk_add_f32 v[216:217], v[120:121], v[216:217]
	v_pk_add_f32 v[218:219], v[122:123], v[218:219]
	v_pk_mul_f32 v[212:213], v[212:213], v[204:205]
	v_pk_mul_f32 v[214:215], v[214:215], v[206:207]
	v_pk_mul_f32 v[216:217], v[216:217], v[208:209]
	v_pk_mul_f32 v[218:219], v[218:219], v[210:211]
	v_pk_mul_f32 v[244:245], v[212:213], v[212:213]
	v_pk_fma_f32 v[244:245], v[214:215], v[214:215], v[244:245]
	v_pk_fma_f32 v[244:245], v[216:217], v[216:217], v[244:245]
	v_pk_fma_f32 v[244:245], v[218:219], v[218:219], v[244:245]
	v_add_f32_e32 v244, v244, v245
	s_nop 1
	v_add_f32_dpp v244, v244, v244 quad_perm:[1,0,3,2] row_mask:0xf bank_mask:0xf
	s_nop 1
	v_add_f32_dpp v244, v244, v244 quad_perm:[2,3,0,1] row_mask:0xf bank_mask:0xf
	s_nop 1
	v_add_f32_dpp v244, v244, v244 row_half_mirror row_mask:0xf bank_mask:0xf
	s_nop 1
	v_add_f32_dpp v244, v244, v244 row_mirror row_mask:0xf bank_mask:0xf
	v_fmamk_f32 v246, v244, 0x3c000000, v242
	v_mul_f32_e32 v248, 0x4b800000, v246
	v_cmp_gt_f32_e32 vcc, s25, v246
	s_nop 1
	v_cndmask_b32_e32 v246, v246, v248, vcc
	v_rsq_f32_e32 v246, v246
	s_nop 0
	v_mul_f32_e32 v248, 0x45800000, v246
	v_cndmask_b32_e32 v246, v246, v248, vcc
	v_pk_mul_f32 v[212:213], v[212:213], v[246:247] op_sel_hi:[1,0]
	v_pk_mul_f32 v[214:215], v[214:215], v[246:247] op_sel_hi:[1,0]
	v_pk_mul_f32 v[216:217], v[216:217], v[246:247] op_sel_hi:[1,0]
	v_pk_mul_f32 v[218:219], v[218:219], v[246:247] op_sel_hi:[1,0]
	v_pk_mul_f32 v[212:213], v[124:125], v[212:213]
	v_pk_mul_f32 v[214:215], v[126:127], v[214:215]
	v_pk_mul_f32 v[216:217], v[128:129], v[216:217]
	v_pk_mul_f32 v[218:219], v[130:131], v[218:219]
	v_cvt_pk_bf16_f32 v68, v212, v213
	v_cvt_pk_bf16_f32 v69, v214, v215
	v_cvt_pk_bf16_f32 v70, v216, v217
	v_cvt_pk_bf16_f32 v71, v218, v219
	global_store_dwordx4 v241, v[68:71], s[18:19]
	s_add_u32 s18, s18, 0x1000
	s_addc_u32 s19, s19, 0
	s_waitcnt vmcnt(4)
	v_lshlrev_b32_e32 v188, 16, v44
	v_and_b32_e32 v189, 0xffff0000, v44
	v_lshlrev_b32_e32 v196, 16, v48
	v_and_b32_e32 v197, 0xffff0000, v48
	v_lshlrev_b32_e32 v190, 16, v45
	v_and_b32_e32 v191, 0xffff0000, v45
	v_lshlrev_b32_e32 v198, 16, v49
	v_and_b32_e32 v199, 0xffff0000, v49
	v_lshlrev_b32_e32 v192, 16, v46
	v_and_b32_e32 v193, 0xffff0000, v46
	v_lshlrev_b32_e32 v200, 16, v50
	v_and_b32_e32 v201, 0xffff0000, v50
	v_lshlrev_b32_e32 v194, 16, v47
	v_and_b32_e32 v195, 0xffff0000, v47
	v_lshlrev_b32_e32 v202, 16, v51
	v_and_b32_e32 v203, 0xffff0000, v51
	v_pk_mul_f32 v[180:181], v[188:189], v[196:197]
	v_pk_mul_f32 v[182:183], v[190:191], v[198:199]
	v_pk_mul_f32 v[184:185], v[192:193], v[200:201]
	v_pk_mul_f32 v[186:187], v[194:195], v[202:203]
	v_lshlrev_b32_e32 v204, 16, v144
	v_and_b32_e32 v205, 0xffff0000, v144
	v_lshlrev_b32_e32 v206, 16, v145
	v_and_b32_e32 v207, 0xffff0000, v145
	v_lshlrev_b32_e32 v208, 16, v146
	v_and_b32_e32 v209, 0xffff0000, v146
	v_lshlrev_b32_e32 v210, 16, v147
	v_and_b32_e32 v211, 0xffff0000, v147
	v_pk_mul_f32 v[68:69], v[100:101], v[172:173]
	v_pk_mul_f32 v[226:227], v[108:109], v[180:181]
	v_pk_mul_f32 v[70:71], v[102:103], v[174:175]
	v_pk_mul_f32 v[228:229], v[110:111], v[182:183]
	v_pk_mul_f32 v[72:73], v[104:105], v[176:177]
	v_pk_mul_f32 v[230:231], v[112:113], v[184:185]
	v_pk_mul_f32 v[74:75], v[106:107], v[178:179]
	v_pk_mul_f32 v[232:233], v[114:115], v[186:187]
	v_pk_fma_f32 v[212:213], v[92:93], v[164:165], v[68:69]
	v_pk_fma_f32 v[214:215], v[94:95], v[166:167], v[70:71]
	v_pk_fma_f32 v[216:217], v[96:97], v[168:169], v[72:73]
	v_pk_fma_f32 v[218:219], v[98:99], v[170:171], v[74:75]
	v_pk_add_f32 v[212:213], v[212:213], v[226:227]
	v_pk_add_f32 v[214:215], v[214:215], v[228:229]
	v_pk_add_f32 v[216:217], v[216:217], v[230:231]
	v_pk_add_f32 v[218:219], v[218:219], v[232:233]
	v_pk_add_f32 v[212:213], v[116:117], v[212:213]
	v_pk_add_f32 v[214:215], v[118:119], v[214:215]
	v_pk_add_f32 v[216:217], v[120:121], v[216:217]
	v_pk_add_f32 v[218:219], v[122:123], v[218:219]
	v_pk_mul_f32 v[212:213], v[212:213], v[204:205]
	v_pk_mul_f32 v[214:215], v[214:215], v[206:207]
	v_pk_mul_f32 v[216:217], v[216:217], v[208:209]
	v_pk_mul_f32 v[218:219], v[218:219], v[210:211]
	v_pk_mul_f32 v[244:245], v[212:213], v[212:213]
	v_pk_fma_f32 v[244:245], v[214:215], v[214:215], v[244:245]
	v_pk_fma_f32 v[244:245], v[216:217], v[216:217], v[244:245]
	v_pk_fma_f32 v[244:245], v[218:219], v[218:219], v[244:245]
	v_add_f32_e32 v244, v244, v245
	s_nop 1
	v_add_f32_dpp v244, v244, v244 quad_perm:[1,0,3,2] row_mask:0xf bank_mask:0xf
	s_nop 1
	v_add_f32_dpp v244, v244, v244 quad_perm:[2,3,0,1] row_mask:0xf bank_mask:0xf
	s_nop 1
	v_add_f32_dpp v244, v244, v244 row_half_mirror row_mask:0xf bank_mask:0xf
	s_nop 1
	v_add_f32_dpp v244, v244, v244 row_mirror row_mask:0xf bank_mask:0xf
	v_fmamk_f32 v246, v244, 0x3c000000, v242
	v_mul_f32_e32 v248, 0x4b800000, v246
	v_cmp_gt_f32_e32 vcc, s25, v246
	s_nop 1
	v_cndmask_b32_e32 v246, v246, v248, vcc
	v_rsq_f32_e32 v246, v246
	s_nop 0
	v_mul_f32_e32 v248, 0x45800000, v246
	v_cndmask_b32_e32 v246, v246, v248, vcc
	v_pk_mul_f32 v[212:213], v[212:213], v[246:247] op_sel_hi:[1,0]
	v_pk_mul_f32 v[214:215], v[214:215], v[246:247] op_sel_hi:[1,0]
	v_pk_mul_f32 v[216:217], v[216:217], v[246:247] op_sel_hi:[1,0]
	v_pk_mul_f32 v[218:219], v[218:219], v[246:247] op_sel_hi:[1,0]
	v_pk_mul_f32 v[212:213], v[124:125], v[212:213]
	v_pk_mul_f32 v[214:215], v[126:127], v[214:215]
	v_pk_mul_f32 v[216:217], v[128:129], v[216:217]
	v_pk_mul_f32 v[218:219], v[130:131], v[218:219]
	v_cvt_pk_bf16_f32 v68, v212, v213
	v_cvt_pk_bf16_f32 v69, v214, v215
	v_cvt_pk_bf16_f32 v70, v216, v217
	v_cvt_pk_bf16_f32 v71, v218, v219
	global_store_dwordx4 v241, v[68:71], s[18:19]
	s_add_u32 s18, s18, 0x1000
	s_addc_u32 s19, s19, 0
	s_waitcnt vmcnt(3)
	v_lshlrev_b32_e32 v188, 16, v52
	v_and_b32_e32 v189, 0xffff0000, v52
	v_lshlrev_b32_e32 v196, 16, v56
	v_and_b32_e32 v197, 0xffff0000, v56
	v_lshlrev_b32_e32 v190, 16, v53
	v_and_b32_e32 v191, 0xffff0000, v53
	v_lshlrev_b32_e32 v198, 16, v57
	v_and_b32_e32 v199, 0xffff0000, v57
	v_lshlrev_b32_e32 v192, 16, v54
	v_and_b32_e32 v193, 0xffff0000, v54
	v_lshlrev_b32_e32 v200, 16, v58
	v_and_b32_e32 v201, 0xffff0000, v58
	v_lshlrev_b32_e32 v194, 16, v55
	v_and_b32_e32 v195, 0xffff0000, v55
	v_lshlrev_b32_e32 v202, 16, v59
	v_and_b32_e32 v203, 0xffff0000, v59
	v_pk_mul_f32 v[164:165], v[188:189], v[196:197]
	v_pk_mul_f32 v[166:167], v[190:191], v[198:199]
	v_pk_mul_f32 v[168:169], v[192:193], v[200:201]
	v_pk_mul_f32 v[170:171], v[194:195], v[202:203]
	v_lshlrev_b32_e32 v204, 16, v148
	v_and_b32_e32 v205, 0xffff0000, v148
	v_lshlrev_b32_e32 v206, 16, v149
	v_and_b32_e32 v207, 0xffff0000, v149
	v_lshlrev_b32_e32 v208, 16, v150
	v_and_b32_e32 v209, 0xffff0000, v150
	v_lshlrev_b32_e32 v210, 16, v151
	v_and_b32_e32 v211, 0xffff0000, v151
	v_pk_mul_f32 v[68:69], v[100:101], v[180:181]
	v_pk_mul_f32 v[226:227], v[108:109], v[164:165]
	v_pk_mul_f32 v[70:71], v[102:103], v[182:183]
	v_pk_mul_f32 v[228:229], v[110:111], v[166:167]
	v_pk_mul_f32 v[72:73], v[104:105], v[184:185]
	v_pk_mul_f32 v[230:231], v[112:113], v[168:169]
	v_pk_mul_f32 v[74:75], v[106:107], v[186:187]
	v_pk_mul_f32 v[232:233], v[114:115], v[170:171]
	v_pk_fma_f32 v[212:213], v[92:93], v[172:173], v[68:69]
	v_pk_fma_f32 v[214:215], v[94:95], v[174:175], v[70:71]
	v_pk_fma_f32 v[216:217], v[96:97], v[176:177], v[72:73]
	v_pk_fma_f32 v[218:219], v[98:99], v[178:179], v[74:75]
	v_pk_add_f32 v[212:213], v[212:213], v[226:227]
	v_pk_add_f32 v[214:215], v[214:215], v[228:229]
	v_pk_add_f32 v[216:217], v[216:217], v[230:231]
	v_pk_add_f32 v[218:219], v[218:219], v[232:233]
	v_pk_add_f32 v[212:213], v[116:117], v[212:213]
	v_pk_add_f32 v[214:215], v[118:119], v[214:215]
	v_pk_add_f32 v[216:217], v[120:121], v[216:217]
	v_pk_add_f32 v[218:219], v[122:123], v[218:219]
	v_pk_mul_f32 v[212:213], v[212:213], v[204:205]
	v_pk_mul_f32 v[214:215], v[214:215], v[206:207]
	v_pk_mul_f32 v[216:217], v[216:217], v[208:209]
	v_pk_mul_f32 v[218:219], v[218:219], v[210:211]
	v_pk_mul_f32 v[244:245], v[212:213], v[212:213]
	v_pk_fma_f32 v[244:245], v[214:215], v[214:215], v[244:245]
	v_pk_fma_f32 v[244:245], v[216:217], v[216:217], v[244:245]
	v_pk_fma_f32 v[244:245], v[218:219], v[218:219], v[244:245]
	v_add_f32_e32 v244, v244, v245
	s_nop 1
	v_add_f32_dpp v244, v244, v244 quad_perm:[1,0,3,2] row_mask:0xf bank_mask:0xf
	s_nop 1
	v_add_f32_dpp v244, v244, v244 quad_perm:[2,3,0,1] row_mask:0xf bank_mask:0xf
	s_nop 1
	v_add_f32_dpp v244, v244, v244 row_half_mirror row_mask:0xf bank_mask:0xf
	s_nop 1
	v_add_f32_dpp v244, v244, v244 row_mirror row_mask:0xf bank_mask:0xf
	v_fmamk_f32 v246, v244, 0x3c000000, v242
	v_mul_f32_e32 v248, 0x4b800000, v246
	v_cmp_gt_f32_e32 vcc, s25, v246
	s_nop 1
	v_cndmask_b32_e32 v246, v246, v248, vcc
	v_rsq_f32_e32 v246, v246
	s_nop 0
	v_mul_f32_e32 v248, 0x45800000, v246
	v_cndmask_b32_e32 v246, v246, v248, vcc
	v_pk_mul_f32 v[212:213], v[212:213], v[246:247] op_sel_hi:[1,0]
	v_pk_mul_f32 v[214:215], v[214:215], v[246:247] op_sel_hi:[1,0]
	v_pk_mul_f32 v[216:217], v[216:217], v[246:247] op_sel_hi:[1,0]
	v_pk_mul_f32 v[218:219], v[218:219], v[246:247] op_sel_hi:[1,0]
	v_pk_mul_f32 v[212:213], v[124:125], v[212:213]
	v_pk_mul_f32 v[214:215], v[126:127], v[214:215]
	v_pk_mul_f32 v[216:217], v[128:129], v[216:217]
	v_pk_mul_f32 v[218:219], v[130:131], v[218:219]
	v_cvt_pk_bf16_f32 v68, v212, v213
	v_cvt_pk_bf16_f32 v69, v214, v215
	v_cvt_pk_bf16_f32 v70, v216, v217
	v_cvt_pk_bf16_f32 v71, v218, v219
	global_store_dwordx4 v241, v[68:71], s[18:19]
	s_add_u32 s18, s18, 0x1000
	s_addc_u32 s19, s19, 0
	s_waitcnt vmcnt(2)
	v_lshlrev_b32_e32 v188, 16, v76
	v_and_b32_e32 v189, 0xffff0000, v76
	v_lshlrev_b32_e32 v196, 16, v80
	v_and_b32_e32 v197, 0xffff0000, v80
	v_lshlrev_b32_e32 v190, 16, v77
	v_and_b32_e32 v191, 0xffff0000, v77
	v_lshlrev_b32_e32 v198, 16, v81
	v_and_b32_e32 v199, 0xffff0000, v81
	v_lshlrev_b32_e32 v192, 16, v78
	v_and_b32_e32 v193, 0xffff0000, v78
	v_lshlrev_b32_e32 v200, 16, v82
	v_and_b32_e32 v201, 0xffff0000, v82
	v_lshlrev_b32_e32 v194, 16, v79
	v_and_b32_e32 v195, 0xffff0000, v79
	v_lshlrev_b32_e32 v202, 16, v83
	v_and_b32_e32 v203, 0xffff0000, v83
	v_pk_mul_f32 v[172:173], v[188:189], v[196:197]
	v_pk_mul_f32 v[174:175], v[190:191], v[198:199]
	v_pk_mul_f32 v[176:177], v[192:193], v[200:201]
	v_pk_mul_f32 v[178:179], v[194:195], v[202:203]
	v_lshlrev_b32_e32 v204, 16, v152
	v_and_b32_e32 v205, 0xffff0000, v152
	v_lshlrev_b32_e32 v206, 16, v153
	v_and_b32_e32 v207, 0xffff0000, v153
	v_lshlrev_b32_e32 v208, 16, v154
	v_and_b32_e32 v209, 0xffff0000, v154
	v_lshlrev_b32_e32 v210, 16, v155
	v_and_b32_e32 v211, 0xffff0000, v155
	v_pk_mul_f32 v[68:69], v[100:101], v[164:165]
	v_pk_mul_f32 v[226:227], v[108:109], v[172:173]
	v_pk_mul_f32 v[70:71], v[102:103], v[166:167]
	v_pk_mul_f32 v[228:229], v[110:111], v[174:175]
	v_pk_mul_f32 v[72:73], v[104:105], v[168:169]
	v_pk_mul_f32 v[230:231], v[112:113], v[176:177]
	v_pk_mul_f32 v[74:75], v[106:107], v[170:171]
	v_pk_mul_f32 v[232:233], v[114:115], v[178:179]
	v_pk_fma_f32 v[212:213], v[92:93], v[180:181], v[68:69]
	v_pk_fma_f32 v[214:215], v[94:95], v[182:183], v[70:71]
	v_pk_fma_f32 v[216:217], v[96:97], v[184:185], v[72:73]
	v_pk_fma_f32 v[218:219], v[98:99], v[186:187], v[74:75]
	v_pk_add_f32 v[212:213], v[212:213], v[226:227]
	v_pk_add_f32 v[214:215], v[214:215], v[228:229]
	v_pk_add_f32 v[216:217], v[216:217], v[230:231]
	v_pk_add_f32 v[218:219], v[218:219], v[232:233]
	v_pk_add_f32 v[212:213], v[116:117], v[212:213]
	v_pk_add_f32 v[214:215], v[118:119], v[214:215]
	v_pk_add_f32 v[216:217], v[120:121], v[216:217]
	v_pk_add_f32 v[218:219], v[122:123], v[218:219]
	v_pk_mul_f32 v[212:213], v[212:213], v[204:205]
	v_pk_mul_f32 v[214:215], v[214:215], v[206:207]
	v_pk_mul_f32 v[216:217], v[216:217], v[208:209]
	v_pk_mul_f32 v[218:219], v[218:219], v[210:211]
	v_pk_mul_f32 v[244:245], v[212:213], v[212:213]
	v_pk_fma_f32 v[244:245], v[214:215], v[214:215], v[244:245]
	v_pk_fma_f32 v[244:245], v[216:217], v[216:217], v[244:245]
	v_pk_fma_f32 v[244:245], v[218:219], v[218:219], v[244:245]
	v_add_f32_e32 v244, v244, v245
	s_nop 1
	v_add_f32_dpp v244, v244, v244 quad_perm:[1,0,3,2] row_mask:0xf bank_mask:0xf
	s_nop 1
	v_add_f32_dpp v244, v244, v244 quad_perm:[2,3,0,1] row_mask:0xf bank_mask:0xf
	s_nop 1
	v_add_f32_dpp v244, v244, v244 row_half_mirror row_mask:0xf bank_mask:0xf
	s_nop 1
	v_add_f32_dpp v244, v244, v244 row_mirror row_mask:0xf bank_mask:0xf
	v_fmamk_f32 v246, v244, 0x3c000000, v242
	v_mul_f32_e32 v248, 0x4b800000, v246
	v_cmp_gt_f32_e32 vcc, s25, v246
	s_nop 1
	v_cndmask_b32_e32 v246, v246, v248, vcc
	v_rsq_f32_e32 v246, v246
	s_nop 0
	v_mul_f32_e32 v248, 0x45800000, v246
	v_cndmask_b32_e32 v246, v246, v248, vcc
	v_pk_mul_f32 v[212:213], v[212:213], v[246:247] op_sel_hi:[1,0]
	v_pk_mul_f32 v[214:215], v[214:215], v[246:247] op_sel_hi:[1,0]
	v_pk_mul_f32 v[216:217], v[216:217], v[246:247] op_sel_hi:[1,0]
	v_pk_mul_f32 v[218:219], v[218:219], v[246:247] op_sel_hi:[1,0]
	v_pk_mul_f32 v[212:213], v[124:125], v[212:213]
	v_pk_mul_f32 v[214:215], v[126:127], v[214:215]
	v_pk_mul_f32 v[216:217], v[128:129], v[216:217]
	v_pk_mul_f32 v[218:219], v[130:131], v[218:219]
	v_cvt_pk_bf16_f32 v68, v212, v213
	v_cvt_pk_bf16_f32 v69, v214, v215
	v_cvt_pk_bf16_f32 v70, v216, v217
	v_cvt_pk_bf16_f32 v71, v218, v219
	global_store_dwordx4 v241, v[68:71], s[18:19]
	s_add_u32 s18, s18, 0x1000
	s_addc_u32 s19, s19, 0
	s_waitcnt vmcnt(1)
	v_lshlrev_b32_e32 v188, 16, v84
	v_and_b32_e32 v189, 0xffff0000, v84
	v_lshlrev_b32_e32 v196, 16, v88
	v_and_b32_e32 v197, 0xffff0000, v88
	v_lshlrev_b32_e32 v190, 16, v85
	v_and_b32_e32 v191, 0xffff0000, v85
	v_lshlrev_b32_e32 v198, 16, v89
	v_and_b32_e32 v199, 0xffff0000, v89
	v_lshlrev_b32_e32 v192, 16, v86
	v_and_b32_e32 v193, 0xffff0000, v86
	v_lshlrev_b32_e32 v200, 16, v90
	v_and_b32_e32 v201, 0xffff0000, v90
	v_lshlrev_b32_e32 v194, 16, v87
	v_and_b32_e32 v195, 0xffff0000, v87
	v_lshlrev_b32_e32 v202, 16, v91
	v_and_b32_e32 v203, 0xffff0000, v91
	v_pk_mul_f32 v[180:181], v[188:189], v[196:197]
	v_pk_mul_f32 v[182:183], v[190:191], v[198:199]
	v_pk_mul_f32 v[184:185], v[192:193], v[200:201]
	v_pk_mul_f32 v[186:187], v[194:195], v[202:203]
	v_lshlrev_b32_e32 v204, 16, v156
	v_and_b32_e32 v205, 0xffff0000, v156
	v_lshlrev_b32_e32 v206, 16, v157
	v_and_b32_e32 v207, 0xffff0000, v157
	v_lshlrev_b32_e32 v208, 16, v158
	v_and_b32_e32 v209, 0xffff0000, v158
	v_lshlrev_b32_e32 v210, 16, v159
	v_and_b32_e32 v211, 0xffff0000, v159
	v_pk_mul_f32 v[68:69], v[100:101], v[172:173]
	v_pk_mul_f32 v[226:227], v[108:109], v[180:181]
	v_pk_mul_f32 v[70:71], v[102:103], v[174:175]
	v_pk_mul_f32 v[228:229], v[110:111], v[182:183]
	v_pk_mul_f32 v[72:73], v[104:105], v[176:177]
	v_pk_mul_f32 v[230:231], v[112:113], v[184:185]
	v_pk_mul_f32 v[74:75], v[106:107], v[178:179]
	v_pk_mul_f32 v[232:233], v[114:115], v[186:187]
	v_pk_fma_f32 v[212:213], v[92:93], v[164:165], v[68:69]
	v_pk_fma_f32 v[214:215], v[94:95], v[166:167], v[70:71]
	v_pk_fma_f32 v[216:217], v[96:97], v[168:169], v[72:73]
	v_pk_fma_f32 v[218:219], v[98:99], v[170:171], v[74:75]
	v_pk_add_f32 v[212:213], v[212:213], v[226:227]
	v_pk_add_f32 v[214:215], v[214:215], v[228:229]
	v_pk_add_f32 v[216:217], v[216:217], v[230:231]
	v_pk_add_f32 v[218:219], v[218:219], v[232:233]
	v_pk_add_f32 v[212:213], v[116:117], v[212:213]
	v_pk_add_f32 v[214:215], v[118:119], v[214:215]
	v_pk_add_f32 v[216:217], v[120:121], v[216:217]
	v_pk_add_f32 v[218:219], v[122:123], v[218:219]
	v_pk_mul_f32 v[212:213], v[212:213], v[204:205]
	v_pk_mul_f32 v[214:215], v[214:215], v[206:207]
	v_pk_mul_f32 v[216:217], v[216:217], v[208:209]
	v_pk_mul_f32 v[218:219], v[218:219], v[210:211]
	v_pk_mul_f32 v[244:245], v[212:213], v[212:213]
	v_pk_fma_f32 v[244:245], v[214:215], v[214:215], v[244:245]
	v_pk_fma_f32 v[244:245], v[216:217], v[216:217], v[244:245]
	v_pk_fma_f32 v[244:245], v[218:219], v[218:219], v[244:245]
	v_add_f32_e32 v244, v244, v245
	s_nop 1
	v_add_f32_dpp v244, v244, v244 quad_perm:[1,0,3,2] row_mask:0xf bank_mask:0xf
	s_nop 1
	v_add_f32_dpp v244, v244, v244 quad_perm:[2,3,0,1] row_mask:0xf bank_mask:0xf
	s_nop 1
	v_add_f32_dpp v244, v244, v244 row_half_mirror row_mask:0xf bank_mask:0xf
	s_nop 1
	v_add_f32_dpp v244, v244, v244 row_mirror row_mask:0xf bank_mask:0xf
	v_fmamk_f32 v246, v244, 0x3c000000, v242
	v_mul_f32_e32 v248, 0x4b800000, v246
	v_cmp_gt_f32_e32 vcc, s25, v246
	s_nop 1
	v_cndmask_b32_e32 v246, v246, v248, vcc
	v_rsq_f32_e32 v246, v246
	s_nop 0
	v_mul_f32_e32 v248, 0x45800000, v246
	v_cndmask_b32_e32 v246, v246, v248, vcc
	v_pk_mul_f32 v[212:213], v[212:213], v[246:247] op_sel_hi:[1,0]
	v_pk_mul_f32 v[214:215], v[214:215], v[246:247] op_sel_hi:[1,0]
	v_pk_mul_f32 v[216:217], v[216:217], v[246:247] op_sel_hi:[1,0]
	v_pk_mul_f32 v[218:219], v[218:219], v[246:247] op_sel_hi:[1,0]
	v_pk_mul_f32 v[212:213], v[124:125], v[212:213]
	v_pk_mul_f32 v[214:215], v[126:127], v[214:215]
	v_pk_mul_f32 v[216:217], v[128:129], v[216:217]
	v_pk_mul_f32 v[218:219], v[130:131], v[218:219]
	v_cvt_pk_bf16_f32 v68, v212, v213
	v_cvt_pk_bf16_f32 v69, v214, v215
	v_cvt_pk_bf16_f32 v70, v216, v217
	v_cvt_pk_bf16_f32 v71, v218, v219
	global_store_dwordx4 v241, v[68:71], s[18:19]
	s_add_u32 s18, s18, 0x1000
	s_addc_u32 s19, s19, 0
	s_waitcnt vmcnt(0)
	s_cmpk_lg_u32 s27, 0xfff
	s_cbranch_scc1 .Lcv_nv_ok
	v_mov_b32_e32 v60, 0
	v_mov_b32_e32 v64, 0
	v_mov_b32_e32 v61, 0
	v_mov_b32_e32 v65, 0
	v_mov_b32_e32 v62, 0
	v_mov_b32_e32 v66, 0
	v_mov_b32_e32 v63, 0
	v_mov_b32_e32 v67, 0
.Lcv_nv_ok:
	v_lshlrev_b32_e32 v188, 16, v60
	v_and_b32_e32 v189, 0xffff0000, v60
	v_lshlrev_b32_e32 v196, 16, v64
	v_and_b32_e32 v197, 0xffff0000, v64
	v_lshlrev_b32_e32 v190, 16, v61
	v_and_b32_e32 v191, 0xffff0000, v61
	v_lshlrev_b32_e32 v198, 16, v65
	v_and_b32_e32 v199, 0xffff0000, v65
	v_lshlrev_b32_e32 v192, 16, v62
	v_and_b32_e32 v193, 0xffff0000, v62
	v_lshlrev_b32_e32 v200, 16, v66
	v_and_b32_e32 v201, 0xffff0000, v66
	v_lshlrev_b32_e32 v194, 16, v63
	v_and_b32_e32 v195, 0xffff0000, v63
	v_lshlrev_b32_e32 v202, 16, v67
	v_and_b32_e32 v203, 0xffff0000, v67
	v_pk_mul_f32 v[164:165], v[188:189], v[196:197]
	v_pk_mul_f32 v[166:167], v[190:191], v[198:199]
	v_pk_mul_f32 v[168:169], v[192:193], v[200:201]
	v_pk_mul_f32 v[170:171], v[194:195], v[202:203]
	v_lshlrev_b32_e32 v204, 16, v160
	v_and_b32_e32 v205, 0xffff0000, v160
	v_lshlrev_b32_e32 v206, 16, v161
	v_and_b32_e32 v207, 0xffff0000, v161
	v_lshlrev_b32_e32 v208, 16, v162
	v_and_b32_e32 v209, 0xffff0000, v162
	v_lshlrev_b32_e32 v210, 16, v163
	v_and_b32_e32 v211, 0xffff0000, v163
	v_pk_mul_f32 v[68:69], v[100:101], v[180:181]
	v_pk_mul_f32 v[226:227], v[108:109], v[164:165]
	v_pk_mul_f32 v[70:71], v[102:103], v[182:183]
	v_pk_mul_f32 v[228:229], v[110:111], v[166:167]
	v_pk_mul_f32 v[72:73], v[104:105], v[184:185]
	v_pk_mul_f32 v[230:231], v[112:113], v[168:169]
	v_pk_mul_f32 v[74:75], v[106:107], v[186:187]
	v_pk_mul_f32 v[232:233], v[114:115], v[170:171]
	v_pk_fma_f32 v[212:213], v[92:93], v[172:173], v[68:69]
	v_pk_fma_f32 v[214:215], v[94:95], v[174:175], v[70:71]
	v_pk_fma_f32 v[216:217], v[96:97], v[176:177], v[72:73]
	v_pk_fma_f32 v[218:219], v[98:99], v[178:179], v[74:75]
	v_pk_add_f32 v[212:213], v[212:213], v[226:227]
	v_pk_add_f32 v[214:215], v[214:215], v[228:229]
	v_pk_add_f32 v[216:217], v[216:217], v[230:231]
	v_pk_add_f32 v[218:219], v[218:219], v[232:233]
	v_pk_add_f32 v[212:213], v[116:117], v[212:213]
	v_pk_add_f32 v[214:215], v[118:119], v[214:215]
	v_pk_add_f32 v[216:217], v[120:121], v[216:217]
	v_pk_add_f32 v[218:219], v[122:123], v[218:219]
	v_pk_mul_f32 v[212:213], v[212:213], v[204:205]
	v_pk_mul_f32 v[214:215], v[214:215], v[206:207]
	v_pk_mul_f32 v[216:217], v[216:217], v[208:209]
	v_pk_mul_f32 v[218:219], v[218:219], v[210:211]
	v_pk_mul_f32 v[244:245], v[212:213], v[212:213]
	v_pk_fma_f32 v[244:245], v[214:215], v[214:215], v[244:245]
	v_pk_fma_f32 v[244:245], v[216:217], v[216:217], v[244:245]
	v_pk_fma_f32 v[244:245], v[218:219], v[218:219], v[244:245]
	v_add_f32_e32 v244, v244, v245
	s_nop 1
	v_add_f32_dpp v244, v244, v244 quad_perm:[1,0,3,2] row_mask:0xf bank_mask:0xf
	s_nop 1
	v_add_f32_dpp v244, v244, v244 quad_perm:[2,3,0,1] row_mask:0xf bank_mask:0xf
	s_nop 1
	v_add_f32_dpp v244, v244, v244 row_half_mirror row_mask:0xf bank_mask:0xf
	s_nop 1
	v_add_f32_dpp v244, v244, v244 row_mirror row_mask:0xf bank_mask:0xf
	v_fmamk_f32 v246, v244, 0x3c000000, v242
	v_mul_f32_e32 v248, 0x4b800000, v246
	v_cmp_gt_f32_e32 vcc, s25, v246
	s_nop 1
	v_cndmask_b32_e32 v246, v246, v248, vcc
	v_rsq_f32_e32 v246, v246
	s_nop 0
	v_mul_f32_e32 v248, 0x45800000, v246
	v_cndmask_b32_e32 v246, v246, v248, vcc
	v_pk_mul_f32 v[212:213], v[212:213], v[246:247] op_sel_hi:[1,0]
	v_pk_mul_f32 v[214:215], v[214:215], v[246:247] op_sel_hi:[1,0]
	v_pk_mul_f32 v[216:217], v[216:217], v[246:247] op_sel_hi:[1,0]
	v_pk_mul_f32 v[218:219], v[218:219], v[246:247] op_sel_hi:[1,0]
	v_pk_mul_f32 v[212:213], v[124:125], v[212:213]
	v_pk_mul_f32 v[214:215], v[126:127], v[214:215]
	v_pk_mul_f32 v[216:217], v[128:129], v[216:217]
	v_pk_mul_f32 v[218:219], v[130:131], v[218:219]
	v_cvt_pk_bf16_f32 v68, v212, v213
	v_cvt_pk_bf16_f32 v69, v214, v215
	v_cvt_pk_bf16_f32 v70, v216, v217
	v_cvt_pk_bf16_f32 v71, v218, v219
	global_store_dwordx4 v241, v[68:71], s[18:19]
	s_add_i32 s20, s20, s30
	s_cmpk_lt_i32 s20, 0x800
	s_cbranch_scc1 .Lcv_item
